# stack v084 with the P10 token barrier guarded by gridDim==256
# baseline (speedup 1.0000x reference)
; __global__ void __launch_bounds__(NT, 2) mk_fwd(Args args) {
;     ...
;         for (int tok = gw; tok < MTOK; tok += NGW) {
.LBB0_886:
	s_cmp_eq_u32 s84, 0x100
	s_cbranch_scc0 .Lp10_nobar
	s_barrier
